# attention loop: scalar look decision, row-max tree trimmed, 3-score live certification before the full row maximum; on top of dynamic range + prologue hoist
# speedup vs baseline: 1.0119x; 1.0006x over previous
.LBB0_300:
	s_or_b64 exec, exec, s[4:5]
	s_lshl_b32 s4, s3, 8
	v_readlane_b32 s5, v245, 15
	s_lshl_b32 s69, s3, 2
	s_ashr_i32 s3, s2, 31
	s_add_i32 s68, s4, s5
	s_lshl_b64 s[2:3], s[2:3], 2
	s_sub_u32 s2, s7, s2
	v_mov_b32_e32 v3, s11
	v_mov_b32_e32 v8, s89
	s_subb_u32 s3, s33, s3
	v_mov_b32_e32 v175, 0
	s_waitcnt lgkmcnt(0)
	s_barrier
	ds_read_b128 v[4:7], v3
	ds_read_b128 v[8:11], v8
	v_and_b32_e32 v185, 31, v19
	v_lshrrev_b32_e32 v3, 1, v19
	v_lshlrev_b32_e32 v172, 2, v2
	v_lshlrev_b32_e32 v12, 7, v185
	v_bitop3_b32 v2, v3, v2, 7 bitop3:0x6c
	v_mul_f32_e32 v18, s12, v235
	v_lshl_add_u32 v186, v2, 4, v12
	v_or_b32_e32 v2, s68, v185
	v_cvt_f32_i32_e32 v3, v172
	v_mul_f32_e32 v173, 0x42800000, v18
	s_mov_b32 s56, 0x41600000
	v_cvt_f32_u32_e32 v2, v2
	v_div_scale_f32 v58, s[2:3], v173, v173, s56
	v_cvt_f32_u32_e32 v13, s4
	v_rcp_f32_e32 v60, v58
	s_waitcnt lgkmcnt(1)
	v_max_f32_e32 v5, v5, v5
	v_max_f32_e32 v4, v4, v4
	v_sub_f32_e32 v187, v3, v2
	v_max_f32_e32 v2, v4, v5
	v_max3_f32 v2, v2, v6, v7
	v_fma_f32 v3, -v58, v60, 1.0
	v_add_f32_e32 v176, v187, v13
	s_waitcnt lgkmcnt(0)
	v_max3_f32 v23, v2, v8, v9
	v_fmac_f32_e32 v60, v3, v60
	v_pk_add_f32 v[2:3], v[176:177], s[14:15] op_sel_hi:[0,1]
	v_max3_f32 v23, v23, v10, v11
	v_and_b32_e32 v24, 0x7fffffff, v2
	s_mov_b32 s2, 0xf800000
	v_and_b32_e32 v25, 0x7fffffff, v3
	v_pk_add_f32 v[12:13], v[176:177], s[22:23] op_sel_hi:[0,1]
	v_pk_add_f32 v[14:15], v[176:177], s[24:25] op_sel_hi:[0,1]
	v_pk_add_f32 v[16:17], v[176:177], s[26:27] op_sel_hi:[0,1]
	v_add_f32_e32 v26, 1.0, v176
	v_and_b32_e32 v11, 0x7fffffff, v13
	v_and_b32_e32 v10, 0x7fffffff, v12
	v_and_b32_e32 v13, 0x7fffffff, v15
	v_and_b32_e32 v12, 0x7fffffff, v14
	v_and_b32_e32 v15, 0x7fffffff, v17
	v_and_b32_e32 v14, 0x7fffffff, v16
	v_and_b32_e32 v22, 0x7fffffff, v176
	v_pk_mul_f32 v[16:17], v[14:15], v[18:19] op_sel_hi:[1,0] neg_lo:[0,1] neg_hi:[0,1]
	v_pk_add_f32 v[8:9], v[176:177], s[20:21] op_sel_hi:[0,1]
	v_and_b32_e32 v9, 0x7fffffff, v9
	v_and_b32_e32 v8, 0x7fffffff, v8
	v_readlane_b32 s55, v245, 28
	v_pk_add_f32 v[4:5], v[176:177], s[16:17] op_sel_hi:[0,1]
	v_pk_add_f32 v[6:7], v[176:177], s[18:19] op_sel_hi:[0,1]
	v_xor_b32_e32 v188, 32, v186
	v_and_b32_e32 v5, 0x7fffffff, v5
	v_and_b32_e32 v4, 0x7fffffff, v4
	v_and_b32_e32 v7, 0x7fffffff, v7
	v_and_b32_e32 v6, 0x7fffffff, v6
	v_add_u32_e32 v61, 0, v188
	v_add_u32_e32 v189, s52, v186
	v_add_u32_e32 v192, s52, v188
	v_div_scale_f32 v59, s[4:5], s56, v173, s56
	v_pk_add_f32 v[42:43], v[176:177], s[28:29] op_sel_hi:[0,1]
	v_pk_add_f32 v[44:45], v[176:177], s[30:31] op_sel_hi:[0,1]
	v_pk_add_f32 v[46:47], v[176:177], s[34:35] op_sel_hi:[0,1]
	v_pk_add_f32 v[48:49], v[176:177], s[36:37] op_sel_hi:[0,1]
	v_pk_add_f32 v[50:51], v[176:177], s[38:39] op_sel_hi:[0,1]
	v_pk_add_f32 v[52:53], v[176:177], s[40:41] op_sel_hi:[0,1]
	v_pk_add_f32 v[54:55], v[176:177], s[42:43] op_sel_hi:[0,1]
	v_pk_add_f32 v[56:57], v[176:177], s[44:45] op_sel_hi:[0,1]
	v_and_b32_e32 v57, 0x7fffffff, v57
	v_and_b32_e32 v56, 0x7fffffff, v56
	v_and_b32_e32 v55, 0x7fffffff, v55
	v_and_b32_e32 v54, 0x7fffffff, v54
	v_and_b32_e32 v53, 0x7fffffff, v53
	v_and_b32_e32 v52, 0x7fffffff, v52
	v_and_b32_e32 v51, 0x7fffffff, v51
	v_and_b32_e32 v50, 0x7fffffff, v50
	v_and_b32_e32 v49, 0x7fffffff, v49
	v_and_b32_e32 v48, 0x7fffffff, v48
	v_and_b32_e32 v47, 0x7fffffff, v47
	v_and_b32_e32 v46, 0x7fffffff, v46
	v_and_b32_e32 v45, 0x7fffffff, v45
	s_waitcnt vmcnt(4)
	v_mul_f32_e32 v2, v23, v249
	v_mul_f32_e32 v3, 0x4f800000, v2
	v_cmp_gt_f32_e32 vcc, s2, v2
	v_and_b32_e32 v23, 0x7fffffff, v26
	v_and_b32_e32 v44, 0x7fffffff, v44
	v_cndmask_b32_e32 v21, v2, v3, vcc
	v_sqrt_f32_e32 v27, v21
	v_pk_mul_f32 v[2:3], v[22:23], v[18:19] op_sel_hi:[1,0] neg_lo:[0,1] neg_hi:[0,1]
	v_and_b32_e32 v43, 0x7fffffff, v43
	v_and_b32_e32 v42, 0x7fffffff, v42
	v_add_u32_e32 v14, -1, v27
	v_add_u32_e32 v15, 1, v27
	v_fma_f32 v22, -v14, v27, v21
	v_fma_f32 v23, -v15, v27, v21
	v_cmp_ge_f32_e64 s[2:3], 0, v22
	v_pk_mul_f32 v[96:97], v[42:43], v[18:19] op_sel_hi:[1,0] neg_lo:[0,1] neg_hi:[0,1]
	v_pk_mul_f32 v[94:95], v[44:45], v[18:19] op_sel_hi:[1,0] neg_lo:[0,1] neg_hi:[0,1]
	v_cndmask_b32_e64 v14, v27, v14, s[2:3]
	v_cmp_lt_f32_e64 s[2:3], 0, v23
	v_pk_mul_f32 v[92:93], v[46:47], v[18:19] op_sel_hi:[1,0] neg_lo:[0,1] neg_hi:[0,1]
	v_pk_mul_f32 v[90:91], v[48:49], v[18:19] op_sel_hi:[1,0] neg_lo:[0,1] neg_hi:[0,1]
	v_cndmask_b32_e64 v14, v14, v15, s[2:3]
	v_mul_f32_e32 v15, 0x37800000, v14
	v_cndmask_b32_e32 v14, v14, v15, vcc
	v_cmp_class_f32_e32 vcc, v21, v232
	v_pk_mul_f32 v[88:89], v[50:51], v[18:19] op_sel_hi:[1,0] neg_lo:[0,1] neg_hi:[0,1]
	v_pk_mul_f32 v[86:87], v[52:53], v[18:19] op_sel_hi:[1,0] neg_lo:[0,1] neg_hi:[0,1]
	v_cndmask_b32_e32 v14, v14, v21, vcc
	v_mul_f32_e32 v21, 0x3f828f5c, v14
	v_add_f32_e32 v246, 0x42000000, v21
	s_nop 0
	v_readfirstlane_b32 s98, v246
	v_fmaak_f32 v22, 2.0, v21, 0x42000000
	v_div_scale_f32 v23, s[2:3], v18, v18, v22
	v_rcp_f32_e32 v26, v23
	v_pk_mul_f32 v[14:15], v[12:13], v[18:19] op_sel_hi:[1,0] neg_lo:[0,1] neg_hi:[0,1]
	v_div_scale_f32 v12, vcc, v22, v18, v22
	v_fma_f32 v13, -v23, v26, 1.0
	v_fmac_f32_e32 v26, v13, v26
	v_mul_f32_e32 v13, v12, v26
	v_fma_f32 v27, -v23, v13, v12
	v_fmac_f32_e32 v13, v27, v26
	v_fma_f32 v12, -v23, v13, v12
	v_div_fmas_f32 v12, v12, v26, v13
	v_div_fixup_f32 v22, v12, v18, v22
	v_cvt_i32_f32_e32 v23, v22
	v_cmp_gt_f32_e32 vcc, s90, v22
	v_pk_mul_f32 v[12:13], v[10:11], v[18:19] op_sel_hi:[1,0] neg_lo:[0,1] neg_hi:[0,1]
	v_pk_mul_f32 v[10:11], v[8:9], v[18:19] op_sel_hi:[1,0] neg_lo:[0,1] neg_hi:[0,1]
	v_readfirstlane_b32 s2, v23
	s_add_i32 s12, s2, 1
	s_and_b64 s[2:3], vcc, exec
	s_cselect_b32 s2, s12, 0x2000
	s_add_i32 s12, s2, 62
	s_add_i32 s2, s2, -2
	s_ashr_i32 s12, s12, 6
	s_ashr_i32 s2, s2, 6
	s_xor_b32 s3, s69, 60
	s_min_i32 s77, s69, s12
	s_add_i32 s2, s2, 1
	s_min_i32 s2, s3, s2
	s_add_i32 s82, s77, 4
	s_add_u32 s12, s80, 0x30000
	s_addc_u32 s13, s81, 0
	s_add_u32 s12, s80, 0x60000
	v_readlane_b32 s13, v245, 27
	s_addc_u32 s13, s81, 0
	v_add_u32_e32 v26, 0, v186
	v_readlane_b32 s12, v245, 29
	v_readlane_b32 s12, v245, 30
	v_pk_mul_f32 v[8:9], v[6:7], v[18:19] op_sel_hi:[1,0] neg_lo:[0,1] neg_hi:[0,1]
	v_pk_mul_f32 v[6:7], v[4:5], v[18:19] op_sel_hi:[1,0] neg_lo:[0,1] neg_hi:[0,1]
	v_pk_mul_f32 v[4:5], v[24:25], v[18:19] op_sel_hi:[1,0] neg_lo:[0,1] neg_hi:[0,1]
	ds_read_b128 v[22:25], v26
	ds_read_b128 v[26:29], v26 offset:4096
	ds_read_b128 v[30:33], v61
	ds_read_b128 v[34:37], v189
	ds_read_b128 v[38:41], v192
	s_waitcnt lgkmcnt(1)
	v_mfma_f32_32x32x16_bf16 v[98:113], v[22:25], v[34:37], v[2:17]
	v_mul_f32_e32 v22, v59, v60
	v_fma_f32 v23, -v58, v22, v59
	v_fmac_f32_e32 v22, v23, v60
	v_mul_f32_e64 v84, v54, -v18
	v_mul_f32_e64 v85, v55, -v18
	v_pk_mul_f32 v[82:83], v[56:57], v[18:19] op_sel_hi:[1,0] neg_lo:[0,1] neg_hi:[0,1]
	v_fma_f32 v23, -v58, v22, v59
	s_mov_b64 vcc, s[4:5]
	v_mfma_f32_32x32x16_bf16 v[82:97], v[26:29], v[34:37], v[82:97]
	v_div_fmas_f32 v26, v23, v60, v22
	ds_read_b128 v[22:25], v61 offset:4096
	v_div_fixup_f32 v26, v26, v173, s56
	v_cmp_gt_f32_e32 vcc, s24, v21
	s_add_i32 s83, s82, s2
	s_cmp_lt_i32 s83, 1
	v_cndmask_b32_e32 v21, 0, v26, vcc
	s_waitcnt lgkmcnt(1)
	v_mfma_f32_32x32x16_bf16 v[98:113], v[30:33], v[38:41], v[98:113]
	v_min_f32_e32 v21, 0x42800000, v21
	s_nop 0
	v_readfirstlane_b32 s3, v21
	s_waitcnt lgkmcnt(0)
	v_mfma_f32_32x32x16_bf16 v[82:97], v[22:25], v[38:41], v[82:97]
	s_cbranch_scc1 .LBB0_350
	v_lshrrev_b32_e32 v21, 2, v19
	v_lshlrev_b32_e32 v19, 1, v19
	v_cvt_i32_f32_e32 v193, s3
	v_and_or_b32 v21, v21, 3, v172
	v_and_or_b32 v19, v19, 32, v20
	v_readfirstlane_b32 s99, v193
	v_lshl_or_b32 v19, v21, 6, v19
	v_mov_b32_e32 v50, v1
	v_mov_b32_e32 v51, v1
	v_mov_b32_e32 v64, v1
	v_mov_b32_e32 v65, v1
	v_xor_b32_e32 v178, 0x80000000, v18
	v_add_u32_e32 v195, 0x2000, v19
	v_mul_f32_e32 v196, 0x42000000, v18
	v_mul_f32_e32 v197, 0xc2000000, v18
	s_add_i32 s86, s2, s77
	v_mov_b32_e32 v52, v1
	v_mov_b32_e32 v53, v1
	v_mov_b32_e32 v54, v1
	v_mov_b32_e32 v55, v1
	v_mov_b32_e32 v56, v1
	v_mov_b32_e32 v57, v1
	v_mov_b32_e32 v58, v1
	v_mov_b32_e32 v59, v1
	v_mov_b32_e32 v60, v1
	v_mov_b32_e32 v61, v1
	v_mov_b32_e32 v62, v1
	v_mov_b32_e32 v63, v1
	v_mov_b64_e32 v[18:19], v[50:51]
	v_mov_b64_e32 v[80:81], v[64:65]
	v_mov_b64_e32 v[34:35], v[50:51]
	v_mov_b32_e32 v180, v178
	v_mov_b32_e32 v181, v178
	v_xor_b32_e32 v194, 64, v186
	s_sub_i32 s84, s69, s77
	s_or_b32 s85, s69, 3
	v_xor_b32_e32 v198, 0x60, v186
	s_add_i32 s86, s86, 4
	s_add_i32 s87, s77, 3
	s_mov_b32 s88, 0
	v_mov_b32_e32 v174, v1
	v_mov_b32_e32 v175, v1
	v_mov_b32_e32 v182, 0
	s_mov_b32 s89, s69
	v_mov_b64_e32 v[20:21], v[52:53]
	v_mov_b64_e32 v[22:23], v[54:55]
	v_mov_b64_e32 v[24:25], v[56:57]
	v_mov_b64_e32 v[26:27], v[58:59]
	v_mov_b64_e32 v[28:29], v[60:61]
	v_mov_b64_e32 v[30:31], v[62:63]
	v_mov_b64_e32 v[32:33], v[64:65]
	v_mov_b64_e32 v[78:79], v[62:63]
	v_mov_b64_e32 v[76:77], v[60:61]
	v_mov_b64_e32 v[74:75], v[58:59]
	v_mov_b64_e32 v[72:73], v[56:57]
	v_mov_b64_e32 v[70:71], v[54:55]
	v_mov_b64_e32 v[68:69], v[52:53]
	v_mov_b64_e32 v[66:67], v[50:51]
	v_mov_b64_e32 v[36:37], v[52:53]
	v_mov_b64_e32 v[38:39], v[54:55]
	v_mov_b64_e32 v[40:41], v[56:57]
	v_mov_b64_e32 v[42:43], v[58:59]
	v_mov_b64_e32 v[44:45], v[60:61]
	v_mov_b64_e32 v[46:47], v[62:63]
	v_mov_b64_e32 v[48:49], v[64:65]
	s_mov_b32 s90, 0
	s_add_i32 s2, s90, 2
	s_cmp_ge_i32 s2, s83
	s_mov_b64 s[2:3], -1
	s_cbranch_scc0 .LBB0_303

.LBB0_314:
	s_waitcnt lgkmcnt(1)
	v_mfma_f32_32x32x16_bf16 v[130:145], v[158:161], v[166:169], v[2:17]
	v_mfma_f32_32x32x16_bf16 v[114:129], v[150:153], v[166:169], v[114:129]
	s_waitcnt lgkmcnt(0)
	v_mfma_f32_32x32x16_bf16 v[130:145], v[154:157], v[162:165], v[130:145]
	v_mfma_f32_32x32x16_bf16 v[114:129], v[146:149], v[162:165], v[114:129]
	s_and_b64 s[4:5], s[4:5], exec
	s_cselect_b32 s4, 0, s77
	s_sub_i32 s4, s90, s4
	s_add_i32 s4, s4, -4
	s_cmp_ge_i32 s4, s99
	s_cselect_b64 s[12:13], -1, 0
	s_or_b64 s[12:13], s[2:3], s[12:13]
	s_not_b64 s[4:5], s[12:13]
	s_mov_b64 s[80:81], -1
	s_cbranch_scc1 .LBB0_319
	s_cmp_lt_u32 s90, 4
	s_cbranch_scc1 .Lq_fullA
	s_cmp_eq_u32 s99, 0
	s_cbranch_scc1 .Lq_fullA
	v_max3_f32 v146, v98, v97, v105
	v_exp_f32_e32 v146, v146
	s_nop 0
	v_mul_f32_e32 v146, 0x4f800000, v146
	v_cmp_ge_f32_e32 vcc, v146, v175
	s_cmp_lg_u64 vcc, 0
	s_cbranch_scc1 .LBB0_319
.Lq_fullA:
	v_max_f32_e32 v148, v100, v84
	v_max3_f32 v146, v98, v82, v102
	v_max3_f32 v149, v101, v85, v105
	v_max3_f32 v148, v148, v104, v88
	v_max3_f32 v147, v99, v83, v103
	v_max3_f32 v146, v146, v86, v106
	v_max3_f32 v149, v149, v89, v109
	v_max3_f32 v148, v148, v108, v92
	v_max3_f32 v147, v147, v87, v107
	v_max3_f32 v146, v146, v90, v110
	v_max3_f32 v149, v149, v93, v113
	v_max3_f32 v148, v148, v112, v96
	v_max3_f32 v147, v147, v91, v111
	v_max3_f32 v146, v146, v94, v95
	v_max3_f32 v148, v148, v97, v149
	v_max3_f32 v146, v146, v147, v148
	v_mov_b32_e32 v147, v146
	s_cmp_eq_u32 s90, 0
	s_nop 0
	v_permlane32_swap_b32_e32 v146, v147
	s_cselect_b64 s[12:13], -1, 0
	s_cmp_lg_u32 s90, 0
	s_cselect_b64 s[56:57], -1, 0
	v_max_f32_e32 v146, v146, v147
	s_and_b64 vcc, exec, s[12:13]
	s_cbranch_vccz .LBB0_347
	s_andn2_b64 vcc, exec, s[56:57]
	s_mov_b64 s[56:57], s[12:13]
	s_cbranch_vccz .LBB0_348

.LBB0_342:
	s_cmp_lt_u32 s90, 4
	s_cbranch_scc1 .Lq_fullB
	s_cmp_eq_u32 s99, 0
	s_cbranch_scc1 .Lq_fullB
	v_max3_f32 v146, v130, v129, v137
	v_exp_f32_e32 v146, v146
	s_nop 0
	v_mul_f32_e32 v146, 0x4f800000, v146
	v_cmp_ge_f32_e32 vcc, v146, v174
	s_cmp_lg_u64 vcc, 0
	s_cbranch_scc1 .LBB0_345
.Lq_fullB:
	v_max_f32_e32 v148, v132, v116
	v_max3_f32 v146, v130, v114, v134
	v_max3_f32 v149, v133, v117, v137
	v_max3_f32 v148, v148, v136, v120
	v_max3_f32 v147, v131, v115, v135
	v_max3_f32 v146, v146, v118, v138
	v_max3_f32 v149, v149, v121, v141
	v_max3_f32 v148, v148, v140, v124
	v_max3_f32 v147, v147, v119, v139
	v_max3_f32 v146, v146, v122, v142
	v_max3_f32 v149, v149, v125, v145
	v_max3_f32 v148, v148, v144, v128
	v_max3_f32 v147, v147, v123, v143
	v_max3_f32 v146, v146, v126, v127
	v_max3_f32 v148, v148, v129, v149
	v_max3_f32 v146, v146, v147, v148
	v_mov_b32_e32 v147, v146
	s_nop 1
	v_permlane32_swap_b32_e32 v146, v147
	s_nop 0
	v_max_f32_e32 v146, v146, v147
	v_exp_f32_e32 v147, v146
	v_cmp_lt_f32_e32 vcc, s20, v146
	v_mul_f32_e32 v147, 0x4f800000, v147
	v_cmp_ge_f32_e64 s[4:5], v147, v174
	s_cbranch_vccz .LBB0_344
	v_max_f32_e32 v146, v146, v146
	v_max_f32_e32 v147, 0, v146
	v_exp_f32_e64 v146, -v147
	v_add_f32_e32 v182, v182, v147
	v_sub_f32_e32 v145, v145, v147
	v_sub_f32_e32 v144, v144, v147
	v_pk_mul_f32 v[174:175], v[174:175], v[146:147] op_sel_hi:[1,0]
	v_sub_f32_e32 v143, v143, v147
	v_sub_f32_e32 v142, v142, v147
	v_sub_f32_e32 v141, v141, v147
	v_sub_f32_e32 v140, v140, v147
	v_sub_f32_e32 v139, v139, v147
	v_sub_f32_e32 v138, v138, v147
	v_sub_f32_e32 v137, v137, v147
	v_sub_f32_e32 v136, v136, v147
	v_sub_f32_e32 v135, v135, v147
	v_sub_f32_e32 v134, v134, v147
	v_sub_f32_e32 v133, v133, v147
	v_sub_f32_e32 v132, v132, v147
	v_sub_f32_e32 v131, v131, v147
	v_sub_f32_e32 v130, v130, v147
	v_sub_f32_e32 v129, v129, v147
	v_sub_f32_e32 v128, v128, v147
	v_sub_f32_e32 v127, v127, v147
	v_sub_f32_e32 v126, v126, v147
	v_sub_f32_e32 v125, v125, v147
	v_sub_f32_e32 v124, v124, v147
	v_sub_f32_e32 v123, v123, v147
	v_sub_f32_e32 v122, v122, v147
	v_sub_f32_e32 v121, v121, v147
	v_sub_f32_e32 v120, v120, v147
	v_sub_f32_e32 v119, v119, v147
	v_sub_f32_e32 v118, v118, v147
	v_sub_f32_e32 v117, v117, v147
	v_sub_f32_e32 v116, v116, v147
	v_sub_f32_e32 v115, v115, v147
	v_sub_f32_e32 v114, v114, v147
	v_sub_f32_e32 v17, v17, v147
	v_sub_f32_e32 v16, v16, v147
	v_sub_f32_e32 v15, v15, v147
	v_sub_f32_e32 v14, v14, v147
	v_sub_f32_e32 v13, v13, v147
	v_sub_f32_e32 v12, v12, v147
	v_sub_f32_e32 v11, v11, v147
	v_sub_f32_e32 v10, v10, v147
	v_sub_f32_e32 v9, v9, v147
	v_sub_f32_e32 v8, v8, v147
	v_sub_f32_e32 v7, v7, v147
	v_sub_f32_e32 v6, v6, v147
	v_sub_f32_e32 v5, v5, v147
	v_sub_f32_e32 v4, v4, v147
	v_sub_f32_e32 v3, v3, v147
	v_sub_f32_e32 v2, v2, v147
	v_sub_f32_e32 v113, v113, v147
	v_sub_f32_e32 v112, v112, v147
	v_sub_f32_e32 v111, v111, v147
	v_sub_f32_e32 v110, v110, v147
	v_sub_f32_e32 v109, v109, v147
	v_sub_f32_e32 v108, v108, v147
	v_sub_f32_e32 v107, v107, v147
	v_sub_f32_e32 v106, v106, v147
	v_sub_f32_e32 v105, v105, v147
	v_sub_f32_e32 v104, v104, v147
	v_sub_f32_e32 v103, v103, v147
	v_sub_f32_e32 v102, v102, v147
	v_sub_f32_e32 v101, v101, v147
	v_sub_f32_e32 v100, v100, v147
	v_sub_f32_e32 v99, v99, v147
	v_sub_f32_e32 v98, v98, v147
	v_sub_f32_e32 v97, v97, v147
	v_sub_f32_e32 v96, v96, v147
	v_sub_f32_e32 v95, v95, v147
	v_sub_f32_e32 v94, v94, v147
	v_sub_f32_e32 v93, v93, v147
	v_sub_f32_e32 v92, v92, v147
	v_sub_f32_e32 v91, v91, v147
	v_sub_f32_e32 v90, v90, v147
	v_sub_f32_e32 v89, v89, v147
	v_sub_f32_e32 v88, v88, v147
	v_sub_f32_e32 v87, v87, v147
	v_sub_f32_e32 v86, v86, v147
	v_sub_f32_e32 v85, v85, v147
	v_sub_f32_e32 v84, v84, v147
	v_sub_f32_e32 v83, v83, v147
	v_sub_f32_e32 v82, v82, v147
	v_pk_mul_f32 v[64:65], v[64:65], v[146:147] op_sel_hi:[1,0]
	v_pk_mul_f32 v[62:63], v[62:63], v[146:147] op_sel_hi:[1,0]
	v_pk_mul_f32 v[60:61], v[60:61], v[146:147] op_sel_hi:[1,0]
	v_pk_mul_f32 v[58:59], v[58:59], v[146:147] op_sel_hi:[1,0]
	v_pk_mul_f32 v[56:57], v[56:57], v[146:147] op_sel_hi:[1,0]
	v_pk_mul_f32 v[54:55], v[54:55], v[146:147] op_sel_hi:[1,0]
	v_pk_mul_f32 v[52:53], v[52:53], v[146:147] op_sel_hi:[1,0]
	v_pk_mul_f32 v[50:51], v[50:51], v[146:147] op_sel_hi:[1,0]
	v_pk_mul_f32 v[32:33], v[32:33], v[146:147] op_sel_hi:[1,0]
	v_pk_mul_f32 v[30:31], v[30:31], v[146:147] op_sel_hi:[1,0]
	v_pk_mul_f32 v[28:29], v[28:29], v[146:147] op_sel_hi:[1,0]
	v_pk_mul_f32 v[26:27], v[26:27], v[146:147] op_sel_hi:[1,0]
	v_pk_mul_f32 v[24:25], v[24:25], v[146:147] op_sel_hi:[1,0]
	v_pk_mul_f32 v[22:23], v[22:23], v[146:147] op_sel_hi:[1,0]
	v_pk_mul_f32 v[20:21], v[20:21], v[146:147] op_sel_hi:[1,0]
	v_pk_mul_f32 v[18:19], v[18:19], v[146:147] op_sel_hi:[1,0]
	v_pk_mul_f32 v[80:81], v[80:81], v[146:147] op_sel_hi:[1,0]
	v_pk_mul_f32 v[78:79], v[78:79], v[146:147] op_sel_hi:[1,0]
	v_pk_mul_f32 v[76:77], v[76:77], v[146:147] op_sel_hi:[1,0]
	v_pk_mul_f32 v[74:75], v[74:75], v[146:147] op_sel_hi:[1,0]
	v_pk_mul_f32 v[72:73], v[72:73], v[146:147] op_sel_hi:[1,0]
	v_pk_mul_f32 v[70:71], v[70:71], v[146:147] op_sel_hi:[1,0]
	v_pk_mul_f32 v[68:69], v[68:69], v[146:147] op_sel_hi:[1,0]
	v_pk_mul_f32 v[66:67], v[66:67], v[146:147] op_sel_hi:[1,0]
	v_pk_mul_f32 v[48:49], v[48:49], v[146:147] op_sel_hi:[1,0]
	v_pk_mul_f32 v[46:47], v[46:47], v[146:147] op_sel_hi:[1,0]
	v_pk_mul_f32 v[44:45], v[44:45], v[146:147] op_sel_hi:[1,0]
	v_pk_mul_f32 v[42:43], v[42:43], v[146:147] op_sel_hi:[1,0]
	v_pk_mul_f32 v[40:41], v[40:41], v[146:147] op_sel_hi:[1,0]
	v_pk_mul_f32 v[38:39], v[38:39], v[146:147] op_sel_hi:[1,0]
	v_pk_mul_f32 v[36:37], v[36:37], v[146:147] op_sel_hi:[1,0]
	v_pk_mul_f32 v[34:35], v[34:35], v[146:147] op_sel_hi:[1,0]

.Ldyn_update:
	v_mov_b32_e32 v246, 0x18080
	ds_read_b32 v246, v246
	v_rcp_f32_e32 v247, v173
	s_waitcnt lgkmcnt(0)
	v_mul_f32_e32 v246, v246, v247
	v_mul_f32_e32 v246, 0x42800800, v246
	v_min_f32_e32 v246, 0x46000000, v246
	v_cvt_i32_f32_e32 v246, v246
	s_nop 0
	v_readfirstlane_b32 s99, v246
	s_add_i32 s99, s99, 2
	s_add_i32 s100, s99, 62
	s_ashr_i32 s100, s100, 6
	s_add_i32 s101, s99, -2
	s_ashr_i32 s101, s101, 6
	s_add_i32 s101, s101, 1
	v_readfirstlane_b32 s99, v193
	s_max_i32 s100, s100, s99
	s_max_i32 s101, s101, s99
	s_max_i32 s100, s100, 3
	s_max_i32 s101, s101, 3
	s_sub_i32 s99, s83, s82
	s_min_i32 s100, s100, s77
	s_min_i32 s101, s101, s99
	s_mov_b32 s77, s100
	s_add_i32 s82, s77, 4
	s_add_i32 s83, s82, s101
	s_mov_b32 s86, s83
	s_sub_i32 s84, s69, s77
	s_add_i32 s87, s77, 3
	v_readfirstlane_b32 s99, v193
	s_branch .Ldyn_back
